# mode-2/mode-3 GEMM epilogues: cache lines of row groups 1..7 touched at epilogue start
# baseline (speedup 1.0000x reference)
; #define PG8_STAGE(bufoff, gbase, voff) do { _Pragma("unroll") for (int _i = 0; _i < 2; ++_i) \
;         __builtin_amdgcn_global_load_lds((const unsigned*)((const char*)(gbase) + (voff)[_i]), (LAS unsigned*)(lds + (bufoff) + ldsw + _i * 8192), 16, 0, 0); } while (0)
; #define PG8_LDA(dst, b, h) do { _Pragma("unroll") for (int m = 0; m < 4; ++m) _Pragma("unroll") for (int k = 0; k < 2; ++k) dst[m][k] = *(const LAS bf16x8*)(lds + PG8_SA(b, h) + aoff + m * 2048 + k * 1024); } while (0)
; #define PG8_LDB(dst, b, h) do { _Pragma("unroll") for (int n = 0; n < 2; ++n) _Pragma("unroll") for (int k = 0; k < 2; ++k) dst[n][k] = *(const LAS bf16x8*)(lds + PG8_SB(b, h) + boff + n * 2048 + k * 1024); } while (0)
; #define PG8_MMA(ai, bj, At, Bt) do { __builtin_amdgcn_s_setprio(1); _Pragma("unroll") for (int m = 0; m < 4; ++m) _Pragma("unroll") for (int n = 0; n < 2; ++n) _Pragma("unroll") for (int k = 0; k < 2; ++k) \
;         acc[ai][bj][m][n] = __builtin_amdgcn_mfma_f32_16x16x32_bf16(Bt[n][k], At[m][k], acc[ai][bj][m][n], 0, 0, 0); __builtin_amdgcn_s_setprio(0); } while (0)
; #define PG8_WAIT_V(n) asm volatile("s_waitcnt vmcnt(" #n ")" ::: "memory")
; #define PG8_WAIT_L(n) asm volatile("s_waitcnt lgkmcnt(" #n ")" ::: "memory")
; #define PG8_BAR __builtin_amdgcn_s_barrier()
; #define PG8_SCHED __builtin_amdgcn_sched_barrier(0)
; DI void gemm_phase(LAS unsigned char* lds, const GemmJob& g, int G, int cidx) {
;     ...
;         for (int t = 0; t < nt; t += 2) {
;             const bool last = (t == nt - 2);
;             const char* a1 = cA + (size_t)(t + 1) * kstep;
;             const char* a2 = last ? nA : cA + (size_t)(t + 2) * kstep; const char* b2 = last ? nB : cB + (size_t)(t + 2) * kstep;
;             const char* a3 = a2 + kstep; const char* b3 = b2 + kstep;
;             PG8_LDB(B0, 0, 0); PG8_SCHED; PG8_LDA(At, 0, 0); PG8_STAGE(PG8_SA(1, 1), a1 + hstepA, voffA);
;             PG8_WAIT_L(8); PG8_BAR; PG8_WAIT_L(0); PG8_MMA(0, 0, At, B0); PG8_BAR; PG8_SCHED;
;             PG8_LDB(B1, 0, 1); PG8_STAGE(PG8_SB(0, 0), b2, voffB);
;             PG8_BAR; PG8_WAIT_L(0); PG8_MMA(0, 1, At, B1); PG8_BAR;
;             PG8_LDA(At, 0, 1); PG8_STAGE(PG8_SA(0, 0), a2, voffA);
;             PG8_BAR; PG8_WAIT_L(0); PG8_MMA(1, 0, At, B0); PG8_BAR; PG8_SCHED;
;             PG8_STAGE(PG8_SB(0, 1), b2 + hstepB, voffB);
;             PG8_WAIT_V(6); PG8_BAR; PG8_MMA(1, 1, At, B1); PG8_BAR;
.LBB0_96:
	s_add_i32 s30, s52, 2
	s_add_u32 s31, s42, 0x80
	s_addc_u32 s53, s43, 0
	s_add_i32 s8, 0, 0x10000
	v_add_u32_e32 v142, s8, v214
	ds_read_b128 v[130:133], v142
	ds_read_b128 v[134:137], v142 offset:1024
	ds_read_b128 v[138:141], v142 offset:2048
	ds_read_b128 v[142:145], v142 offset:3072
	s_cmp_eq_u32 s67, s52
	s_cselect_b32 s52, s94, s31
	s_cselect_b32 s53, s95, s53
	s_cselect_b32 s93, s45, vcc_hi
	s_cselect_b32 s92, s44, vcc_lo
	v_lshl_add_u64 v[226:227], s[42:43], 0, v[176:177]
	s_add_i32 m0, s29, 0xc000
	ds_read_b128 v[146:149], v217
	ds_read_b128 v[150:153], v217 offset:1024
	ds_read_b128 v[154:157], v217 offset:2048
	ds_read_b128 v[164:167], v217 offset:3072
	ds_read_b128 v[180:183], v217 offset:4096
	ds_read_b128 v[184:187], v217 offset:5120
	ds_read_b128 v[218:221], v217 offset:6144
	ds_read_b128 v[222:225], v217 offset:7168
	global_load_lds_dwordx4 v[226:227], off
	v_lshl_add_u64 v[226:227], s[42:43], 0, v[178:179]
	s_add_i32 m0, s29, 0xe000
	s_nop 0
	global_load_lds_dwordx4 v[226:227], off
	s_waitcnt lgkmcnt(8)
	s_barrier
	s_waitcnt lgkmcnt(0)
	s_setprio 1
	s_waitcnt lgkmcnt(0)
	v_mfma_f32_16x16x32_bf16 v[126:129], v[130:133], v[146:149], v[126:129]
	v_mfma_f32_16x16x32_bf16 v[122:125], v[138:141], v[146:149], v[122:125]
	v_mfma_f32_16x16x32_bf16 v[118:121], v[130:133], v[154:157], v[118:121]
	v_mfma_f32_16x16x32_bf16 v[114:117], v[138:141], v[154:157], v[114:117]
	v_mfma_f32_16x16x32_bf16 v[102:105], v[130:133], v[180:183], v[102:105]
	v_mfma_f32_16x16x32_bf16 v[98:101], v[138:141], v[180:183], v[98:101]
	v_mfma_f32_16x16x32_bf16 v[86:89], v[130:133], v[218:221], v[86:89]
	v_mfma_f32_16x16x32_bf16 v[82:85], v[138:141], v[218:221], v[82:85]
	v_mfma_f32_16x16x32_bf16 v[126:129], v[134:137], v[150:153], v[126:129]
	v_mfma_f32_16x16x32_bf16 v[122:125], v[142:145], v[150:153], v[122:125]
	v_mfma_f32_16x16x32_bf16 v[118:121], v[134:137], v[164:167], v[118:121]
	v_mfma_f32_16x16x32_bf16 v[114:117], v[142:145], v[164:167], v[114:117]
	v_mfma_f32_16x16x32_bf16 v[102:105], v[134:137], v[184:187], v[102:105]
	v_mfma_f32_16x16x32_bf16 v[98:101], v[142:145], v[184:187], v[98:101]
	v_mfma_f32_16x16x32_bf16 v[86:89], v[134:137], v[222:225], v[86:89]
	v_mfma_f32_16x16x32_bf16 v[82:85], v[142:145], v[222:225], v[82:85]
	s_setprio 0
	s_barrier
	s_add_i32 s9, 0, 0x14000
	s_add_i32 s8, s8, s28
	v_add_u32_e32 v192, s9, v214
	v_lshl_add_u64 v[242:243], s[92:93], 0, v[0:1]
	s_mov_b32 m0, s8
	ds_read_b128 v[226:229], v192
	ds_read_b128 v[230:233], v192 offset:1024
	ds_read_b128 v[234:237], v192 offset:2048
	ds_read_b128 v[238:241], v192 offset:3072
	global_load_lds_dwordx4 v[242:243], off
	v_lshl_add_u64 v[244:245], s[92:93], 0, v[172:173]
	s_add_i32 m0, s8, 0x2000
	s_nop 0
	global_load_lds_dwordx4 v[244:245], off
	s_barrier
	s_waitcnt lgkmcnt(0)
	s_setprio 1
	s_waitcnt lgkmcnt(0)
	v_mfma_f32_16x16x32_bf16 v[110:113], v[226:229], v[146:149], v[110:113]
	v_mfma_f32_16x16x32_bf16 v[106:109], v[234:237], v[146:149], v[106:109]
	v_mfma_f32_16x16x32_bf16 v[94:97], v[226:229], v[154:157], v[94:97]
	v_mfma_f32_16x16x32_bf16 v[90:93], v[234:237], v[154:157], v[90:93]
	v_mfma_f32_16x16x32_bf16 v[78:81], v[226:229], v[180:183], v[78:81]
	v_mfma_f32_16x16x32_bf16 v[74:77], v[234:237], v[180:183], v[74:77]
	v_mfma_f32_16x16x32_bf16 v[70:73], v[226:229], v[218:221], v[70:73]
	v_mfma_f32_16x16x32_bf16 v[66:69], v[234:237], v[218:221], v[66:69]
	v_mfma_f32_16x16x32_bf16 v[110:113], v[230:233], v[150:153], v[110:113]
	v_mfma_f32_16x16x32_bf16 v[106:109], v[238:241], v[150:153], v[106:109]
	v_mfma_f32_16x16x32_bf16 v[94:97], v[230:233], v[164:167], v[94:97]
	v_mfma_f32_16x16x32_bf16 v[90:93], v[238:241], v[164:167], v[90:93]
	v_mfma_f32_16x16x32_bf16 v[78:81], v[230:233], v[184:187], v[78:81]
	v_mfma_f32_16x16x32_bf16 v[74:77], v[238:241], v[184:187], v[74:77]
	v_mfma_f32_16x16x32_bf16 v[70:73], v[230:233], v[222:225], v[70:73]
	v_mfma_f32_16x16x32_bf16 v[66:69], v[238:241], v[222:225], v[66:69]
	s_setprio 0
	s_mov_b32 m0, s29
	v_lshl_add_u64 v[246:247], s[52:53], 0, v[174:175]
	s_barrier
	ds_read_b128 v[146:149], v217 offset:16384
	ds_read_b128 v[150:153], v217 offset:17408
	ds_read_b128 v[154:157], v217 offset:18432
	ds_read_b128 v[164:167], v217 offset:19456
	ds_read_b128 v[180:183], v217 offset:20480
	ds_read_b128 v[184:187], v217 offset:21504
	ds_read_b128 v[218:221], v217 offset:22528
	ds_read_b128 v[222:225], v217 offset:23552
	global_load_lds_dwordx4 v[246:247], off
	v_lshl_add_u64 v[192:193], s[52:53], 0, v[158:159]
	s_mov_b32 m0, s96
	s_nop 0
	global_load_lds_dwordx4 v[192:193], off
	s_barrier
	s_waitcnt lgkmcnt(0)
	s_setprio 1
	s_waitcnt lgkmcnt(0)
	v_mfma_f32_16x16x32_bf16 v[62:65], v[130:133], v[146:149], v[62:65]
	v_mfma_f32_16x16x32_bf16 v[58:61], v[138:141], v[146:149], v[58:61]
	v_mfma_f32_16x16x32_bf16 v[54:57], v[130:133], v[154:157], v[54:57]
	v_mfma_f32_16x16x32_bf16 v[50:53], v[138:141], v[154:157], v[50:53]
	v_mfma_f32_16x16x32_bf16 v[38:41], v[130:133], v[180:183], v[38:41]
	v_mfma_f32_16x16x32_bf16 v[34:37], v[138:141], v[180:183], v[34:37]
	v_mfma_f32_16x16x32_bf16 v[22:25], v[130:133], v[218:221], v[22:25]
	v_mfma_f32_16x16x32_bf16 v[18:21], v[138:141], v[218:221], v[18:21]
	v_mfma_f32_16x16x32_bf16 v[62:65], v[134:137], v[150:153], v[62:65]
	v_mfma_f32_16x16x32_bf16 v[58:61], v[142:145], v[150:153], v[58:61]
	v_mfma_f32_16x16x32_bf16 v[54:57], v[134:137], v[164:167], v[54:57]
	v_mfma_f32_16x16x32_bf16 v[50:53], v[142:145], v[164:167], v[50:53]
	v_mfma_f32_16x16x32_bf16 v[38:41], v[134:137], v[184:187], v[38:41]
	v_mfma_f32_16x16x32_bf16 v[34:37], v[142:145], v[184:187], v[34:37]
	v_mfma_f32_16x16x32_bf16 v[22:25], v[134:137], v[222:225], v[22:25]
	v_mfma_f32_16x16x32_bf16 v[18:21], v[142:145], v[222:225], v[18:21]
	s_setprio 0
	s_barrier
; #define PG8_STAGE(bufoff, gbase, voff) do { _Pragma("unroll") for (int _i = 0; _i < 2; ++_i) \
;         __builtin_amdgcn_global_load_lds((const unsigned*)((const char*)(gbase) + (voff)[_i]), (LAS unsigned*)(lds + (bufoff) + ldsw + _i * 8192), 16, 0, 0); } while (0)
; #define PG8_LDA(dst, b, h) do { _Pragma("unroll") for (int m = 0; m < 4; ++m) _Pragma("unroll") for (int k = 0; k < 2; ++k) dst[m][k] = *(const LAS bf16x8*)(lds + PG8_SA(b, h) + aoff + m * 2048 + k * 1024); } while (0)
; #define PG8_LDB(dst, b, h) do { _Pragma("unroll") for (int n = 0; n < 2; ++n) _Pragma("unroll") for (int k = 0; k < 2; ++k) dst[n][k] = *(const LAS bf16x8*)(lds + PG8_SB(b, h) + boff + n * 2048 + k * 1024); } while (0)
; #define PG8_MMA(ai, bj, At, Bt) do { __builtin_amdgcn_s_setprio(1); _Pragma("unroll") for (int m = 0; m < 4; ++m) _Pragma("unroll") for (int n = 0; n < 2; ++n) _Pragma("unroll") for (int k = 0; k < 2; ++k) \
;         acc[ai][bj][m][n] = __builtin_amdgcn_mfma_f32_16x16x32_bf16(Bt[n][k], At[m][k], acc[ai][bj][m][n], 0, 0, 0); __builtin_amdgcn_s_setprio(0); } while (0)
; #define PG8_WAIT_V(n) asm volatile("s_waitcnt vmcnt(" #n ")" ::: "memory")
; #define PG8_WAIT_L(n) asm volatile("s_waitcnt lgkmcnt(" #n ")" ::: "memory")
; #define PG8_BAR __builtin_amdgcn_s_barrier()
; #define PG8_SCHED __builtin_amdgcn_sched_barrier(0)
; DI void gemm_phase(LAS unsigned char* lds, const GemmJob& g, int G, int cidx) {
;     ...
;             PG8_BAR; PG8_WAIT_L(0); PG8_MMA(1, 0, At, B0); PG8_BAR; PG8_SCHED;
;             PG8_STAGE(PG8_SB(0, 1), b2 + hstepB, voffB);
;             PG8_WAIT_V(6); PG8_BAR; PG8_MMA(1, 1, At, B1); PG8_BAR;
;             PG8_LDB(B0, 1, 0); PG8_SCHED; PG8_LDA(At, 1, 0); PG8_STAGE(PG8_SA(0, 1), a2 + hstepA, voffA);
;             PG8_WAIT_L(8); PG8_BAR; PG8_WAIT_L(0); PG8_MMA(0, 0, At, B0); PG8_BAR; PG8_SCHED;
;             PG8_LDB(B1, 1, 1); PG8_STAGE(PG8_SB(1, 0), b3, voffB);
;             PG8_BAR; PG8_WAIT_L(0); PG8_MMA(0, 1, At, B1); PG8_BAR;
;             PG8_LDA(At, 1, 1); PG8_STAGE(PG8_SA(1, 0), a3, voffA);
;             PG8_BAR; PG8_WAIT_L(0); PG8_MMA(1, 0, At, B0); PG8_BAR; PG8_SCHED;
	s_add_u32 s92, s92, s82
	s_addc_u32 s93, s93, s83
	s_add_i32 s8, s9, s28
	v_lshl_add_u64 v[204:205], s[92:93], 0, v[0:1]
	s_mov_b32 m0, s8
	v_lshl_add_u64 v[206:207], s[92:93], 0, v[172:173]
	global_load_lds_dwordx4 v[204:205], off
	s_add_i32 m0, s8, 0x2000
	s_nop 0
	global_load_lds_dwordx4 v[206:207], off
	s_waitcnt vmcnt(6)
	s_barrier
	s_setprio 1
	v_mfma_f32_16x16x32_bf16 v[46:49], v[226:229], v[146:149], v[46:49]
	v_mfma_f32_16x16x32_bf16 v[42:45], v[234:237], v[146:149], v[42:45]
	v_mfma_f32_16x16x32_bf16 v[30:33], v[226:229], v[154:157], v[30:33]
	v_mfma_f32_16x16x32_bf16 v[26:29], v[234:237], v[154:157], v[26:29]
	v_mfma_f32_16x16x32_bf16 v[14:17], v[226:229], v[180:183], v[14:17]
	v_mfma_f32_16x16x32_bf16 v[10:13], v[234:237], v[180:183], v[10:13]
	v_mfma_f32_16x16x32_bf16 v[6:9], v[226:229], v[218:221], v[6:9]
	v_mfma_f32_16x16x32_bf16 v[2:5], v[234:237], v[218:221], v[2:5]
	v_mfma_f32_16x16x32_bf16 v[46:49], v[230:233], v[150:153], v[46:49]
	v_mfma_f32_16x16x32_bf16 v[42:45], v[238:241], v[150:153], v[42:45]
	v_mfma_f32_16x16x32_bf16 v[30:33], v[230:233], v[164:167], v[30:33]
	v_mfma_f32_16x16x32_bf16 v[26:29], v[238:241], v[164:167], v[26:29]
	v_mfma_f32_16x16x32_bf16 v[14:17], v[230:233], v[184:187], v[14:17]
	v_mfma_f32_16x16x32_bf16 v[10:13], v[238:241], v[184:187], v[10:13]
	v_mfma_f32_16x16x32_bf16 v[6:9], v[230:233], v[222:225], v[6:9]
	v_mfma_f32_16x16x32_bf16 v[2:5], v[238:241], v[222:225], v[2:5]
	s_setprio 0
	s_add_i32 s8, 0, 0x18000
	v_add_u32_e32 v142, s8, v214
	s_barrier
	ds_read_b128 v[130:133], v142
	ds_read_b128 v[134:137], v142 offset:1024
	ds_read_b128 v[138:141], v142 offset:2048
	ds_read_b128 v[142:145], v142 offset:3072
	s_add_u32 s52, s52, s82
	s_addc_u32 s53, s53, s83
	s_mov_b32 m0, s97
	v_lshl_add_u64 v[226:227], s[52:53], 0, v[174:175]
	ds_read_b128 v[146:149], v217 offset:32768
	ds_read_b128 v[150:153], v217 offset:33792
	ds_read_b128 v[154:157], v217 offset:34816
	ds_read_b128 v[164:167], v217 offset:35840
	ds_read_b128 v[180:183], v217 offset:36864
	ds_read_b128 v[184:187], v217 offset:37888
	ds_read_b128 v[218:221], v217 offset:38912
	ds_read_b128 v[222:225], v217 offset:39936
	global_load_lds_dwordx4 v[226:227], off
	v_lshl_add_u64 v[226:227], s[52:53], 0, v[158:159]
	s_mov_b32 m0, s22
	s_nop 0
	global_load_lds_dwordx4 v[226:227], off
	s_waitcnt lgkmcnt(8)
	s_barrier
	s_waitcnt lgkmcnt(0)
	s_setprio 1
	s_waitcnt lgkmcnt(0)
	v_mfma_f32_16x16x32_bf16 v[126:129], v[130:133], v[146:149], v[126:129]
	v_mfma_f32_16x16x32_bf16 v[122:125], v[138:141], v[146:149], v[122:125]
	v_mfma_f32_16x16x32_bf16 v[118:121], v[130:133], v[154:157], v[118:121]
	v_mfma_f32_16x16x32_bf16 v[114:117], v[138:141], v[154:157], v[114:117]
	v_mfma_f32_16x16x32_bf16 v[102:105], v[130:133], v[180:183], v[102:105]
	v_mfma_f32_16x16x32_bf16 v[98:101], v[138:141], v[180:183], v[98:101]
	v_mfma_f32_16x16x32_bf16 v[86:89], v[130:133], v[218:221], v[86:89]
	v_mfma_f32_16x16x32_bf16 v[82:85], v[138:141], v[218:221], v[82:85]
	v_mfma_f32_16x16x32_bf16 v[126:129], v[134:137], v[150:153], v[126:129]
	v_mfma_f32_16x16x32_bf16 v[122:125], v[142:145], v[150:153], v[122:125]
	v_mfma_f32_16x16x32_bf16 v[118:121], v[134:137], v[164:167], v[118:121]
	v_mfma_f32_16x16x32_bf16 v[114:117], v[142:145], v[164:167], v[114:117]
	v_mfma_f32_16x16x32_bf16 v[102:105], v[134:137], v[184:187], v[102:105]
	v_mfma_f32_16x16x32_bf16 v[98:101], v[142:145], v[184:187], v[98:101]
	v_mfma_f32_16x16x32_bf16 v[86:89], v[134:137], v[222:225], v[86:89]
	v_mfma_f32_16x16x32_bf16 v[82:85], v[142:145], v[222:225], v[82:85]
	s_setprio 0
	s_barrier
	s_add_i32 s9, 0, 0x1c000
	s_add_i32 s8, s8, s28
	v_add_u32_e32 v238, s9, v214
	v_lshl_add_u64 v[242:243], v[242:243], 0, s[90:91]
	s_mov_b32 m0, s8
	ds_read_b128 v[226:229], v238
	ds_read_b128 v[230:233], v238 offset:1024
	ds_read_b128 v[234:237], v238 offset:2048
	ds_read_b128 v[238:241], v238 offset:3072
	global_load_lds_dwordx4 v[242:243], off
	v_lshl_add_u64 v[242:243], v[244:245], 0, s[90:91]
	s_add_i32 m0, s8, 0x2000
	s_nop 0
	global_load_lds_dwordx4 v[242:243], off
	s_barrier
	s_waitcnt lgkmcnt(0)
	s_setprio 1
	s_waitcnt lgkmcnt(0)
	v_mfma_f32_16x16x32_bf16 v[110:113], v[226:229], v[146:149], v[110:113]
	v_mfma_f32_16x16x32_bf16 v[106:109], v[234:237], v[146:149], v[106:109]
	v_mfma_f32_16x16x32_bf16 v[94:97], v[226:229], v[154:157], v[94:97]
	v_mfma_f32_16x16x32_bf16 v[90:93], v[234:237], v[154:157], v[90:93]
	v_mfma_f32_16x16x32_bf16 v[78:81], v[226:229], v[180:183], v[78:81]
	v_mfma_f32_16x16x32_bf16 v[74:77], v[234:237], v[180:183], v[74:77]
	v_mfma_f32_16x16x32_bf16 v[70:73], v[226:229], v[218:221], v[70:73]
	v_mfma_f32_16x16x32_bf16 v[66:69], v[234:237], v[218:221], v[66:69]
	v_mfma_f32_16x16x32_bf16 v[110:113], v[230:233], v[150:153], v[110:113]
	v_mfma_f32_16x16x32_bf16 v[106:109], v[238:241], v[150:153], v[106:109]
	v_mfma_f32_16x16x32_bf16 v[94:97], v[230:233], v[164:167], v[94:97]
	v_mfma_f32_16x16x32_bf16 v[90:93], v[238:241], v[164:167], v[90:93]
	v_mfma_f32_16x16x32_bf16 v[78:81], v[230:233], v[184:187], v[78:81]
	v_mfma_f32_16x16x32_bf16 v[74:77], v[238:241], v[184:187], v[74:77]
	v_mfma_f32_16x16x32_bf16 v[70:73], v[230:233], v[222:225], v[70:73]
	v_mfma_f32_16x16x32_bf16 v[66:69], v[238:241], v[222:225], v[66:69]
	s_setprio 0
	s_mov_b32 m0, s23
	v_lshl_add_u64 v[242:243], v[246:247], 0, s[90:91]
	s_barrier
	ds_read_b128 v[146:149], v217 offset:49152
	ds_read_b128 v[150:153], v217 offset:50176
	ds_read_b128 v[154:157], v217 offset:51200
	ds_read_b128 v[164:167], v217 offset:52224
	ds_read_b128 v[180:183], v217 offset:53248
	ds_read_b128 v[184:187], v217 offset:54272
	ds_read_b128 v[218:221], v217 offset:55296
	ds_read_b128 v[222:225], v217 offset:56320
	global_load_lds_dwordx4 v[242:243], off
	v_lshl_add_u64 v[192:193], v[192:193], 0, s[90:91]
	s_mov_b32 m0, s34
	s_nop 0
	global_load_lds_dwordx4 v[192:193], off
	s_barrier
; #define PG8_STAGE(bufoff, gbase, voff) do { _Pragma("unroll") for (int _i = 0; _i < 2; ++_i) \
;         __builtin_amdgcn_global_load_lds((const unsigned*)((const char*)(gbase) + (voff)[_i]), (LAS unsigned*)(lds + (bufoff) + ldsw + _i * 8192), 16, 0, 0); } while (0)
; #define PG8_LDA(dst, b, h) do { _Pragma("unroll") for (int m = 0; m < 4; ++m) _Pragma("unroll") for (int k = 0; k < 2; ++k) dst[m][k] = *(const LAS bf16x8*)(lds + PG8_SA(b, h) + aoff + m * 2048 + k * 1024); } while (0)
; #define PG8_WAIT_V(n) asm volatile("s_waitcnt vmcnt(" #n ")" ::: "memory")
; #define PG8_WAIT_L(n) asm volatile("s_waitcnt lgkmcnt(" #n ")" ::: "memory")
; #define PG8_BAR __builtin_amdgcn_s_barrier()
; #define PG8_SCHED __builtin_amdgcn_sched_barrier(0)
; DI void gemm_epilogue(const GemmJob& J, const f32x4 (&acc)[2][2][4][2], const pg8::Unit& u, int wr, int wc, int fr, int fq) {
;     ...
;         bf16_t* X = (bf16_t*)J.o1;
;         u32x2 xb[2][4]; f32x4 gg[2][4];
;         { const float* gp = J.f1 + (size_t)modrow_of(J.row0 + rloc0) * 12288;
; #pragma unroll
;           for (int q = 0; q < 4; ++q) { const int col = u.pn * 256 + (q >> 1) * 128 + wc * 32 + (q & 1) * 16 + 4 * fq; xb[0][q] = *(const u32x2*)(X + (size_t)rloc0 * J.ld1 + col); gg[0][q] = *(const f32x4*)(gp + col); } }
; #pragma unroll
;         for (int it = 0; it < 8; ++it) { const int ai = it >> 2, m = it & 3; const int row = rloc0 + ai * 128 + m * 16;
;             if (it + 1 < 8) { const int rown = rloc0 + ((it + 1) >> 2) * 128 + ((it + 1) & 3) * 16; const float* gp = J.f1 + (size_t)modrow_of(J.row0 + rown) * 12288;
; #pragma unroll
;                 for (int q = 0; q < 4; ++q) { const int col = u.pn * 256 + (q >> 1) * 128 + wc * 32 + (q & 1) * 16 + 4 * fq; xb[(it + 1) & 1][q] = *(const u32x2*)(X + (size_t)rown * J.ld1 + col); gg[(it + 1) & 1][q] = *(const f32x4*)(gp + col); } }
; DI void gemm_phase(LAS unsigned char* lds, const GemmJob& g, int G, int cidx) {
;     ...
;             PG8_BAR; PG8_WAIT_L(0); PG8_MMA(0, 1, At, B1); PG8_BAR;
;             PG8_LDA(At, 1, 1); PG8_STAGE(PG8_SA(1, 0), a3, voffA);
;             PG8_BAR; PG8_WAIT_L(0); PG8_MMA(1, 0, At, B0); PG8_BAR; PG8_SCHED;
;             PG8_STAGE(PG8_SB(1, 1), b3 + hstepB, voffB);
;             PG8_WAIT_V(6); PG8_BAR; PG8_MMA(1, 1, At, B1); PG8_BAR;
;         }
;         gemm_epilogue(g, acc, cur, wr, wc, fr, fq);
	s_waitcnt lgkmcnt(0)
	s_setprio 1
	s_waitcnt lgkmcnt(0)
	v_mfma_f32_16x16x32_bf16 v[62:65], v[130:133], v[146:149], v[62:65]
	v_mfma_f32_16x16x32_bf16 v[58:61], v[138:141], v[146:149], v[58:61]
	v_mfma_f32_16x16x32_bf16 v[54:57], v[130:133], v[154:157], v[54:57]
	v_mfma_f32_16x16x32_bf16 v[50:53], v[138:141], v[154:157], v[50:53]
	v_mfma_f32_16x16x32_bf16 v[38:41], v[130:133], v[180:183], v[38:41]
	v_mfma_f32_16x16x32_bf16 v[34:37], v[138:141], v[180:183], v[34:37]
	v_mfma_f32_16x16x32_bf16 v[22:25], v[130:133], v[218:221], v[22:25]
	v_mfma_f32_16x16x32_bf16 v[18:21], v[138:141], v[218:221], v[18:21]
	v_mfma_f32_16x16x32_bf16 v[62:65], v[134:137], v[150:153], v[62:65]
	v_mfma_f32_16x16x32_bf16 v[58:61], v[142:145], v[150:153], v[58:61]
	v_mfma_f32_16x16x32_bf16 v[54:57], v[134:137], v[164:167], v[54:57]
	v_mfma_f32_16x16x32_bf16 v[50:53], v[142:145], v[164:167], v[50:53]
	v_mfma_f32_16x16x32_bf16 v[38:41], v[134:137], v[184:187], v[38:41]
	v_mfma_f32_16x16x32_bf16 v[34:37], v[142:145], v[184:187], v[34:37]
	v_mfma_f32_16x16x32_bf16 v[22:25], v[134:137], v[222:225], v[22:25]
	v_mfma_f32_16x16x32_bf16 v[18:21], v[142:145], v[222:225], v[18:21]
	s_setprio 0
	s_barrier
	s_add_i32 s8, s9, s28
	v_lshl_add_u64 v[130:131], v[204:205], 0, s[90:91]
	s_mov_b32 m0, s8
	s_nop 0
	global_load_lds_dwordx4 v[130:131], off
	v_lshl_add_u64 v[130:131], v[206:207], 0, s[90:91]
	s_add_i32 m0, s8, 0x2000
	s_nop 0
	global_load_lds_dwordx4 v[130:131], off
	s_waitcnt vmcnt(6)
	s_barrier
	s_setprio 1
	v_mfma_f32_16x16x32_bf16 v[46:49], v[226:229], v[146:149], v[46:49]
	v_mfma_f32_16x16x32_bf16 v[42:45], v[234:237], v[146:149], v[42:45]
	v_mfma_f32_16x16x32_bf16 v[30:33], v[226:229], v[154:157], v[30:33]
	v_mfma_f32_16x16x32_bf16 v[26:29], v[234:237], v[154:157], v[26:29]
	v_mfma_f32_16x16x32_bf16 v[14:17], v[226:229], v[180:183], v[14:17]
	v_mfma_f32_16x16x32_bf16 v[10:13], v[234:237], v[180:183], v[10:13]
	v_mfma_f32_16x16x32_bf16 v[6:9], v[226:229], v[218:221], v[6:9]
	v_mfma_f32_16x16x32_bf16 v[2:5], v[234:237], v[218:221], v[2:5]
	v_mfma_f32_16x16x32_bf16 v[46:49], v[230:233], v[150:153], v[46:49]
	v_mfma_f32_16x16x32_bf16 v[42:45], v[238:241], v[150:153], v[42:45]
	v_mfma_f32_16x16x32_bf16 v[30:33], v[230:233], v[164:167], v[30:33]
	v_mfma_f32_16x16x32_bf16 v[26:29], v[238:241], v[164:167], v[26:29]
	v_mfma_f32_16x16x32_bf16 v[14:17], v[230:233], v[184:187], v[14:17]
	v_mfma_f32_16x16x32_bf16 v[10:13], v[238:241], v[184:187], v[10:13]
	v_mfma_f32_16x16x32_bf16 v[6:9], v[230:233], v[222:225], v[6:9]
	v_mfma_f32_16x16x32_bf16 v[2:5], v[238:241], v[222:225], v[2:5]
	s_setprio 0
	s_add_u32 s42, s42, 0x100
	s_addc_u32 s43, s43, 0
	s_add_u32 vcc_lo, vcc_lo, 0x100
	s_addc_u32 vcc_hi, vcc_hi, 0
	s_cmp_ge_u32 s30, s35
	s_mov_b32 s52, s30
	s_barrier
	s_cbranch_scc0 .LBB0_96
	v_lshl_add_u32 v218, s25, 8, v213
	s_cmp_lt_i32 s74, 2
	s_mov_b64 s[42:43], -1
	s_cbranch_scc1 .LBB0_135
	s_cmp_gt_i32 s74, 2
	s_cbranch_scc0 .LBB0_100
	v_add_u32_e32 v130, 0xffffc000, v218
	v_lshrrev_b32_e32 v130, 4, v130
	v_or_b32_e32 v130, 1, v130
	v_cmp_lt_i32_e32 vcc, s3, v218
	v_add_u32_e32 v152, 0xffffc010, v218
	v_lshl_or_b32 v138, s84, 8, v216
	v_cndmask_b32_e32 v132, 0, v130, vcc
	v_mov_b64_e32 v[130:131], s[12:13]
	v_mad_u64_u32 v[136:137], s[30:31], v132, s86, v[130:131]
	v_ashrrev_i32_e32 v132, 31, v218
	v_mul_lo_u32 v192, v132, s27
	v_mad_u64_u32 v[132:133], s[30:31], v218, s27, 0
	v_or_b32_e32 v154, 16, v218
	v_lshrrev_b32_e32 v152, 4, v152
	v_add_u32_e32 v133, v133, v192
	v_ashrrev_i32_e32 v139, 31, v138
	v_add_u32_e32 v152, 1, v152
	v_cmp_lt_i32_e32 vcc, s3, v154
	v_lshl_add_u64 v[134:135], v[132:133], 1, s[54:55]
	v_lshlrev_b64 v[132:133], 1, v[138:139]
	v_cndmask_b32_e32 v152, 0, v152, vcc
	v_mad_u64_u32 v[154:155], s[30:31], v154, s27, 0
	v_lshl_add_u64 v[156:157], v[134:135], 0, v[132:133]
	v_lshlrev_b64 v[134:135], 2, v[138:139]
	v_mad_u64_u32 v[152:153], s[30:31], v152, s86, v[130:131]
	v_add_u32_e32 v155, v155, v192
	v_lshl_add_u64 v[148:149], v[136:137], 0, v[134:135]
	v_lshl_add_u64 v[154:155], v[154:155], 1, s[54:55]
	v_lshl_add_u64 v[184:185], v[152:153], 0, v[134:135]
	s_mov_b64 s[30:31], 0x8000
	v_lshl_add_u64 v[240:241], v[156:157], 0, s[30:31]
	global_load_dword v219, v[240:241], off
	global_load_dword v219, v[240:241], off offset:256
	s_mov_b64 s[30:31], 0x10000
	v_lshl_add_u64 v[240:241], v[156:157], 0, s[30:31]
	global_load_dword v219, v[240:241], off
	global_load_dword v219, v[240:241], off offset:256
	s_mov_b64 s[30:31], 0x18000
	v_lshl_add_u64 v[240:241], v[156:157], 0, s[30:31]
	global_load_dword v219, v[240:241], off
	global_load_dword v219, v[240:241], off offset:256
	s_mov_b64 s[30:31], 0x40000
	v_lshl_add_u64 v[240:241], v[156:157], 0, s[30:31]
	global_load_dword v219, v[240:241], off
	global_load_dword v219, v[240:241], off offset:256
	s_mov_b64 s[30:31], 0x48000
	v_lshl_add_u64 v[240:241], v[156:157], 0, s[30:31]
	global_load_dword v219, v[240:241], off
	global_load_dword v219, v[240:241], off offset:256
	s_mov_b64 s[30:31], 0x50000
	v_lshl_add_u64 v[240:241], v[156:157], 0, s[30:31]
	global_load_dword v219, v[240:241], off
	global_load_dword v219, v[240:241], off offset:256
	s_mov_b64 s[30:31], 0x58000
	v_lshl_add_u64 v[240:241], v[156:157], 0, s[30:31]
	global_load_dword v219, v[240:241], off
	global_load_dword v219, v[240:241], off offset:256
	global_load_dwordx4 v[136:139], v[148:149], off
	global_load_dwordx4 v[140:143], v[148:149], off offset:64
	global_load_dwordx2 v[220:221], v[156:157], off
	global_load_dwordx2 v[222:223], v[156:157], off offset:32
	global_load_dwordx2 v[224:225], v[156:157], off offset:256
	global_load_dwordx2 v[226:227], v[156:157], off offset:288
	global_load_dwordx4 v[144:147], v[148:149], off offset:512
	s_nop 0
	global_load_dwordx4 v[148:151], v[148:149], off offset:576
	v_lshl_add_u64 v[228:229], v[154:155], 0, v[132:133]
	global_load_dwordx4 v[152:155], v[184:185], off
	global_load_dwordx4 v[164:167], v[184:185], off offset:64
	global_load_dwordx2 v[230:231], v[228:229], off
	global_load_dwordx2 v[232:233], v[228:229], off offset:32
	global_load_dwordx2 v[234:235], v[228:229], off offset:256
	global_load_dwordx2 v[236:237], v[228:229], off offset:288
	global_load_dwordx4 v[180:183], v[184:185], off offset:512
	s_nop 0
	global_load_dwordx4 v[184:187], v[184:185], off offset:576
	s_waitcnt vmcnt(0)
; DI unsigned pk2(float lo, float hi) { const hwf2_t v = {lo, hi}; const hwbf2_t b = __builtin_convertvector(v, hwbf2_t); return __builtin_bit_cast(unsigned, b); }
; DI float lo16(unsigned w) { return __uint_as_float(w << 16); }
; DI float hi16(unsigned w) { return __uint_as_float(w & 0xffff0000u); }
; DI void gemm_epilogue(const GemmJob& J, const f32x4 (&acc)[2][2][4][2], const pg8::Unit& u, int wr, int wc, int fr, int fq) {
;     ...
; #pragma unroll
;         for (int it = 0; it < 8; ++it) { const int ai = it >> 2, m = it & 3; const int row = rloc0 + ai * 128 + m * 16;
;             if (it + 1 < 8) { const int rown = rloc0 + ((it + 1) >> 2) * 128 + ((it + 1) & 3) * 16; const float* gp = J.f1 + (size_t)modrow_of(J.row0 + rown) * 12288;
; #pragma unroll
;                 for (int q = 0; q < 4; ++q) { const int col = u.pn * 256 + (q >> 1) * 128 + wc * 32 + (q & 1) * 16 + 4 * fq; xb[(it + 1) & 1][q] = *(const u32x2*)(X + (size_t)rown * J.ld1 + col); gg[(it + 1) & 1][q] = *(const f32x4*)(gp + col); } }
;             __builtin_amdgcn_sched_barrier(0);
; #pragma unroll
;             for (int q = 0; q < 4; ++q) { const int bj = q >> 1, n = q & 1; const int col = u.pn * 256 + bj * 128 + wc * 32 + n * 16 + 4 * fq;
;                 const u32x2 xw = xb[it & 1][q]; const f32x4 xv = (f32x4){lo16(xw.x), hi16(xw.x), lo16(xw.y), hi16(xw.y)};
;                 const f32x4 o = xv * DN_ALPHA + (gg[it & 1][q] + 1.0f) * acc[ai][bj][m][n];
;                 u32x2 w; w.x = pk2(o[0], o[1]); w.y = pk2(o[2], o[3]); *(u32x2*)(X + (size_t)row * J.ld1 + col) = w; }
;             __builtin_amdgcn_sched_barrier(0); }
	v_lshlrev_b32_e32 v238, 16, v220
	v_and_b32_e32 v239, 0xffff0000, v220
	v_lshlrev_b32_e32 v220, 16, v221
	v_and_b32_e32 v221, 0xffff0000, v221
	v_pk_mul_f32 v[238:239], v[238:239], s[10:11] op_sel_hi:[1,0]
	v_pk_mul_f32 v[220:221], v[220:221], s[10:11] op_sel_hi:[1,0]
	v_pk_add_f32 v[138:139], v[138:139], 1.0 op_sel_hi:[1,0]
	v_pk_add_f32 v[136:137], v[136:137], 1.0 op_sel_hi:[1,0]
	v_pk_fma_f32 v[138:139], v[128:129], v[138:139], v[220:221]
	v_pk_fma_f32 v[136:137], v[126:127], v[136:137], v[238:239]
	v_pk_add_f32 v[142:143], v[142:143], 1.0 op_sel_hi:[1,0]
	v_cvt_pk_bf16_f32 v136, v136, v137
	v_cvt_pk_bf16_f32 v137, v138, v139
	global_store_dwordx2 v[156:157], v[136:137], off
	v_lshlrev_b32_e32 v136, 16, v222
	v_and_b32_e32 v137, 0xffff0000, v222
	v_lshlrev_b32_e32 v138, 16, v223
	v_and_b32_e32 v139, 0xffff0000, v223
	v_pk_mul_f32 v[136:137], v[136:137], s[10:11] op_sel_hi:[1,0]
	v_pk_mul_f32 v[138:139], v[138:139], s[10:11] op_sel_hi:[1,0]
	v_pk_add_f32 v[140:141], v[140:141], 1.0 op_sel_hi:[1,0]
	v_pk_fma_f32 v[138:139], v[124:125], v[142:143], v[138:139]
	v_pk_fma_f32 v[136:137], v[122:123], v[140:141], v[136:137]
	v_pk_add_f32 v[140:141], v[146:147], 1.0 op_sel_hi:[1,0]
	v_cvt_pk_bf16_f32 v136, v136, v137
	v_cvt_pk_bf16_f32 v137, v138, v139
	global_store_dwordx2 v[156:157], v[136:137], off offset:32
	v_lshlrev_b32_e32 v136, 16, v224
	v_and_b32_e32 v137, 0xffff0000, v224
	v_lshlrev_b32_e32 v138, 16, v225
	v_and_b32_e32 v139, 0xffff0000, v225
	v_pk_mul_f32 v[136:137], v[136:137], s[10:11] op_sel_hi:[1,0]
	v_pk_mul_f32 v[138:139], v[138:139], s[10:11] op_sel_hi:[1,0]
	v_pk_add_f32 v[142:143], v[144:145], 1.0 op_sel_hi:[1,0]
	v_pk_fma_f32 v[138:139], v[112:113], v[140:141], v[138:139]
	v_pk_fma_f32 v[136:137], v[110:111], v[142:143], v[136:137]
	v_pk_add_f32 v[140:141], v[150:151], 1.0 op_sel_hi:[1,0]
	v_cvt_pk_bf16_f32 v136, v136, v137
	v_cvt_pk_bf16_f32 v137, v138, v139
	global_store_dwordx2 v[156:157], v[136:137], off offset:256
	v_lshlrev_b32_e32 v136, 16, v226
	v_and_b32_e32 v137, 0xffff0000, v226
	v_lshlrev_b32_e32 v138, 16, v227
	v_and_b32_e32 v139, 0xffff0000, v227
	v_pk_mul_f32 v[136:137], v[136:137], s[10:11] op_sel_hi:[1,0]
	v_pk_mul_f32 v[138:139], v[138:139], s[10:11] op_sel_hi:[1,0]
	v_pk_add_f32 v[142:143], v[148:149], 1.0 op_sel_hi:[1,0]
	v_pk_fma_f32 v[138:139], v[108:109], v[140:141], v[138:139]
	v_pk_fma_f32 v[136:137], v[106:107], v[142:143], v[136:137]
	s_nop 0
	v_cvt_pk_bf16_f32 v136, v136, v137
	v_cvt_pk_bf16_f32 v137, v138, v139
	global_store_dwordx2 v[156:157], v[136:137], off offset:288
	v_add_u32_e32 v136, 0xffffc020, v218
	v_or_b32_e32 v138, 32, v218
	v_lshrrev_b32_e32 v136, 4, v136
	v_or_b32_e32 v136, 1, v136
	v_cmp_lt_i32_e32 vcc, s3, v138
	v_mad_u64_u32 v[138:139], s[30:31], v138, s27, 0
	s_nop 0
	v_cndmask_b32_e32 v136, 0, v136, vcc
	v_mad_u64_u32 v[136:137], s[30:31], v136, s86, v[130:131]
	v_add_u32_e32 v139, v139, v192
	v_lshl_add_u64 v[138:139], v[138:139], 1, s[54:55]
	v_lshl_add_u64 v[148:149], v[136:137], 0, v[134:135]
	v_lshl_add_u64 v[156:157], v[138:139], 0, v[132:133]
	global_load_dwordx4 v[136:139], v[148:149], off
	global_load_dwordx4 v[140:143], v[148:149], off offset:64
	global_load_dwordx2 v[220:221], v[156:157], off
	global_load_dwordx2 v[222:223], v[156:157], off offset:32
	global_load_dwordx2 v[224:225], v[156:157], off offset:256
	global_load_dwordx2 v[226:227], v[156:157], off offset:288
	global_load_dwordx4 v[144:147], v[148:149], off offset:512
	s_nop 0
	global_load_dwordx4 v[148:151], v[148:149], off offset:576
	v_lshlrev_b32_e32 v238, 16, v230
	v_and_b32_e32 v239, 0xffff0000, v230
	v_lshlrev_b32_e32 v230, 16, v231
	v_and_b32_e32 v231, 0xffff0000, v231
	v_pk_mul_f32 v[238:239], v[238:239], s[10:11] op_sel_hi:[1,0]
	v_pk_mul_f32 v[230:231], v[230:231], s[10:11] op_sel_hi:[1,0]
	v_pk_add_f32 v[154:155], v[154:155], 1.0 op_sel_hi:[1,0]
	v_pk_add_f32 v[152:153], v[152:153], 1.0 op_sel_hi:[1,0]
	v_pk_fma_f32 v[154:155], v[120:121], v[154:155], v[230:231]
	v_pk_fma_f32 v[152:153], v[118:119], v[152:153], v[238:239]
	v_pk_add_f32 v[166:167], v[166:167], 1.0 op_sel_hi:[1,0]
	v_cvt_pk_bf16_f32 v152, v152, v153
	v_cvt_pk_bf16_f32 v153, v154, v155
	global_store_dwordx2 v[228:229], v[152:153], off
	v_lshlrev_b32_e32 v152, 16, v232
	v_and_b32_e32 v153, 0xffff0000, v232
	v_lshlrev_b32_e32 v154, 16, v233
	v_and_b32_e32 v155, 0xffff0000, v233
	v_pk_mul_f32 v[152:153], v[152:153], s[10:11] op_sel_hi:[1,0]
	v_pk_mul_f32 v[154:155], v[154:155], s[10:11] op_sel_hi:[1,0]
	v_pk_add_f32 v[164:165], v[164:165], 1.0 op_sel_hi:[1,0]
	v_pk_fma_f32 v[154:155], v[116:117], v[166:167], v[154:155]
	v_pk_fma_f32 v[152:153], v[114:115], v[164:165], v[152:153]
	v_pk_add_f32 v[164:165], v[182:183], 1.0 op_sel_hi:[1,0]
	v_cvt_pk_bf16_f32 v152, v152, v153
	v_cvt_pk_bf16_f32 v153, v154, v155
	global_store_dwordx2 v[228:229], v[152:153], off offset:32
	v_lshlrev_b32_e32 v152, 16, v234
	v_and_b32_e32 v153, 0xffff0000, v234
	v_lshlrev_b32_e32 v154, 16, v235
	v_and_b32_e32 v155, 0xffff0000, v235
	v_pk_mul_f32 v[152:153], v[152:153], s[10:11] op_sel_hi:[1,0]
	v_pk_mul_f32 v[154:155], v[154:155], s[10:11] op_sel_hi:[1,0]
	v_pk_add_f32 v[166:167], v[180:181], 1.0 op_sel_hi:[1,0]
	v_pk_fma_f32 v[154:155], v[96:97], v[164:165], v[154:155]
	v_pk_fma_f32 v[152:153], v[94:95], v[166:167], v[152:153]
	v_pk_add_f32 v[164:165], v[186:187], 1.0 op_sel_hi:[1,0]
	v_cvt_pk_bf16_f32 v152, v152, v153
	v_cvt_pk_bf16_f32 v153, v154, v155
	global_store_dwordx2 v[228:229], v[152:153], off offset:256
	v_lshlrev_b32_e32 v152, 16, v236
	v_and_b32_e32 v153, 0xffff0000, v236
	v_lshlrev_b32_e32 v154, 16, v237
	v_and_b32_e32 v155, 0xffff0000, v237
; DI unsigned pk2(float lo, float hi) { const hwf2_t v = {lo, hi}; const hwbf2_t b = __builtin_convertvector(v, hwbf2_t); return __builtin_bit_cast(unsigned, b); }
; DI float lo16(unsigned w) { return __uint_as_float(w << 16); }
; DI float hi16(unsigned w) { return __uint_as_float(w & 0xffff0000u); }
; DI void gemm_epilogue(const GemmJob& J, const f32x4 (&acc)[2][2][4][2], const pg8::Unit& u, int wr, int wc, int fr, int fq) {
;     ...
; #pragma unroll
;         for (int it = 0; it < 8; ++it) { const int ai = it >> 2, m = it & 3; const int row = rloc0 + ai * 128 + m * 16;
;             if (it + 1 < 8) { const int rown = rloc0 + ((it + 1) >> 2) * 128 + ((it + 1) & 3) * 16; const float* gp = J.f1 + (size_t)modrow_of(J.row0 + rown) * 12288;
; #pragma unroll
;                 for (int q = 0; q < 4; ++q) { const int col = u.pn * 256 + (q >> 1) * 128 + wc * 32 + (q & 1) * 16 + 4 * fq; xb[(it + 1) & 1][q] = *(const u32x2*)(X + (size_t)rown * J.ld1 + col); gg[(it + 1) & 1][q] = *(const f32x4*)(gp + col); } }
;             __builtin_amdgcn_sched_barrier(0);
; #pragma unroll
;             for (int q = 0; q < 4; ++q) { const int bj = q >> 1, n = q & 1; const int col = u.pn * 256 + bj * 128 + wc * 32 + n * 16 + 4 * fq;
;                 const u32x2 xw = xb[it & 1][q]; const f32x4 xv = (f32x4){lo16(xw.x), hi16(xw.x), lo16(xw.y), hi16(xw.y)};
;                 const f32x4 o = xv * DN_ALPHA + (gg[it & 1][q] + 1.0f) * acc[ai][bj][m][n];
;                 u32x2 w; w.x = pk2(o[0], o[1]); w.y = pk2(o[2], o[3]); *(u32x2*)(X + (size_t)row * J.ld1 + col) = w; }
;             __builtin_amdgcn_sched_barrier(0); }
	v_pk_mul_f32 v[152:153], v[152:153], s[10:11] op_sel_hi:[1,0]
	v_pk_mul_f32 v[154:155], v[154:155], s[10:11] op_sel_hi:[1,0]
	v_pk_add_f32 v[166:167], v[184:185], 1.0 op_sel_hi:[1,0]
	v_pk_fma_f32 v[154:155], v[92:93], v[164:165], v[154:155]
	v_pk_fma_f32 v[152:153], v[90:91], v[166:167], v[152:153]
	s_nop 0
	v_cvt_pk_bf16_f32 v152, v152, v153
	v_cvt_pk_bf16_f32 v153, v154, v155
	global_store_dwordx2 v[228:229], v[152:153], off offset:288
	v_add_u32_e32 v152, 0xffffc030, v218
	v_or_b32_e32 v154, 48, v218
	v_lshrrev_b32_e32 v152, 4, v152
	v_add_u32_e32 v152, 1, v152
	v_cmp_lt_i32_e32 vcc, s3, v154
	v_mad_u64_u32 v[154:155], s[30:31], v154, s27, 0
	s_nop 0
	v_cndmask_b32_e32 v152, 0, v152, vcc
	v_mad_u64_u32 v[152:153], s[30:31], v152, s86, v[130:131]
	v_add_u32_e32 v155, v155, v192
	v_lshl_add_u64 v[154:155], v[154:155], 1, s[54:55]
	v_lshl_add_u64 v[184:185], v[152:153], 0, v[134:135]
	v_lshl_add_u64 v[228:229], v[154:155], 0, v[132:133]
	global_load_dwordx4 v[152:155], v[184:185], off
	global_load_dwordx4 v[164:167], v[184:185], off offset:64
	global_load_dwordx2 v[230:231], v[228:229], off
	global_load_dwordx2 v[232:233], v[228:229], off offset:32
	global_load_dwordx2 v[234:235], v[228:229], off offset:256
	global_load_dwordx2 v[236:237], v[228:229], off offset:288
	global_load_dwordx4 v[180:183], v[184:185], off offset:512
	s_nop 0
	global_load_dwordx4 v[184:187], v[184:185], off offset:576
	s_waitcnt vmcnt(0)
	v_lshlrev_b32_e32 v238, 16, v220
	v_and_b32_e32 v239, 0xffff0000, v220
	v_lshlrev_b32_e32 v220, 16, v221
	v_and_b32_e32 v221, 0xffff0000, v221
	v_pk_mul_f32 v[238:239], v[238:239], s[10:11] op_sel_hi:[1,0]
	v_pk_mul_f32 v[220:221], v[220:221], s[10:11] op_sel_hi:[1,0]
	v_pk_add_f32 v[138:139], v[138:139], 1.0 op_sel_hi:[1,0]
	v_pk_add_f32 v[136:137], v[136:137], 1.0 op_sel_hi:[1,0]
	v_pk_fma_f32 v[138:139], v[104:105], v[138:139], v[220:221]
	v_pk_fma_f32 v[136:137], v[102:103], v[136:137], v[238:239]
	v_pk_add_f32 v[142:143], v[142:143], 1.0 op_sel_hi:[1,0]
	v_cvt_pk_bf16_f32 v136, v136, v137
	v_cvt_pk_bf16_f32 v137, v138, v139
	global_store_dwordx2 v[156:157], v[136:137], off
	v_lshlrev_b32_e32 v136, 16, v222
	v_and_b32_e32 v137, 0xffff0000, v222
	v_lshlrev_b32_e32 v138, 16, v223
	v_and_b32_e32 v139, 0xffff0000, v223
	v_pk_mul_f32 v[136:137], v[136:137], s[10:11] op_sel_hi:[1,0]
	v_pk_mul_f32 v[138:139], v[138:139], s[10:11] op_sel_hi:[1,0]
	v_pk_add_f32 v[140:141], v[140:141], 1.0 op_sel_hi:[1,0]
	v_pk_fma_f32 v[138:139], v[100:101], v[142:143], v[138:139]
	v_pk_fma_f32 v[136:137], v[98:99], v[140:141], v[136:137]
	v_pk_add_f32 v[140:141], v[146:147], 1.0 op_sel_hi:[1,0]
	v_cvt_pk_bf16_f32 v136, v136, v137
	v_cvt_pk_bf16_f32 v137, v138, v139
	global_store_dwordx2 v[156:157], v[136:137], off offset:32
	v_lshlrev_b32_e32 v136, 16, v224
	v_and_b32_e32 v137, 0xffff0000, v224
	v_lshlrev_b32_e32 v138, 16, v225
	v_and_b32_e32 v139, 0xffff0000, v225
	v_pk_mul_f32 v[136:137], v[136:137], s[10:11] op_sel_hi:[1,0]
	v_pk_mul_f32 v[138:139], v[138:139], s[10:11] op_sel_hi:[1,0]
	v_pk_add_f32 v[142:143], v[144:145], 1.0 op_sel_hi:[1,0]
	v_pk_fma_f32 v[138:139], v[80:81], v[140:141], v[138:139]
	v_pk_fma_f32 v[136:137], v[78:79], v[142:143], v[136:137]
	v_pk_add_f32 v[140:141], v[150:151], 1.0 op_sel_hi:[1,0]
	v_cvt_pk_bf16_f32 v136, v136, v137
	v_cvt_pk_bf16_f32 v137, v138, v139
	global_store_dwordx2 v[156:157], v[136:137], off offset:256
	v_lshlrev_b32_e32 v136, 16, v226
	v_and_b32_e32 v137, 0xffff0000, v226
	v_lshlrev_b32_e32 v138, 16, v227
	v_and_b32_e32 v139, 0xffff0000, v227
	v_pk_mul_f32 v[136:137], v[136:137], s[10:11] op_sel_hi:[1,0]
	v_pk_mul_f32 v[138:139], v[138:139], s[10:11] op_sel_hi:[1,0]
	v_pk_add_f32 v[142:143], v[148:149], 1.0 op_sel_hi:[1,0]
	v_pk_fma_f32 v[138:139], v[76:77], v[140:141], v[138:139]
	v_pk_fma_f32 v[136:137], v[74:75], v[142:143], v[136:137]
	s_nop 0
	v_cvt_pk_bf16_f32 v136, v136, v137
	v_cvt_pk_bf16_f32 v137, v138, v139
	global_store_dwordx2 v[156:157], v[136:137], off offset:288
	v_add_u32_e32 v138, 0x80, v218
	v_add_u32_e32 v136, 0xffffc080, v218
	v_lshrrev_b32_e32 v136, 4, v136
	s_movk_i32 s25, 0x3f7f
	v_ashrrev_i32_e32 v141, 31, v138
	v_mad_u64_u32 v[138:139], s[30:31], v138, s27, 0
	v_or_b32_e32 v136, 1, v136
	v_cmp_lt_i32_e32 vcc, s25, v218
	v_mov_b32_e32 v140, v139
	v_mad_u64_u32 v[140:141], s[30:31], v141, s27, v[140:141]
	v_cndmask_b32_e32 v136, 0, v136, vcc
	v_mad_u64_u32 v[136:137], s[30:31], v136, s86, v[130:131]
	v_mov_b32_e32 v139, v140
	v_lshl_add_u64 v[138:139], v[138:139], 1, s[54:55]
	v_lshl_add_u64 v[148:149], v[136:137], 0, v[134:135]
	v_lshl_add_u64 v[156:157], v[138:139], 0, v[132:133]
	global_load_dwordx4 v[136:139], v[148:149], off
	global_load_dwordx4 v[140:143], v[148:149], off offset:64
	global_load_dwordx2 v[220:221], v[156:157], off
	global_load_dwordx2 v[222:223], v[156:157], off offset:32
	global_load_dwordx2 v[224:225], v[156:157], off offset:256
	global_load_dwordx2 v[226:227], v[156:157], off offset:288
	global_load_dwordx4 v[144:147], v[148:149], off offset:512
	s_nop 0
	global_load_dwordx4 v[148:151], v[148:149], off offset:576
	v_lshlrev_b32_e32 v238, 16, v230
	v_and_b32_e32 v239, 0xffff0000, v230
	v_lshlrev_b32_e32 v230, 16, v231
	v_and_b32_e32 v231, 0xffff0000, v231
	v_pk_mul_f32 v[238:239], v[238:239], s[10:11] op_sel_hi:[1,0]
	v_pk_mul_f32 v[230:231], v[230:231], s[10:11] op_sel_hi:[1,0]
	v_pk_add_f32 v[154:155], v[154:155], 1.0 op_sel_hi:[1,0]
	v_pk_add_f32 v[152:153], v[152:153], 1.0 op_sel_hi:[1,0]
	v_pk_fma_f32 v[154:155], v[88:89], v[154:155], v[230:231]
	v_pk_fma_f32 v[152:153], v[86:87], v[152:153], v[238:239]
	v_pk_add_f32 v[166:167], v[166:167], 1.0 op_sel_hi:[1,0]
; DI unsigned pk2(float lo, float hi) { const hwf2_t v = {lo, hi}; const hwbf2_t b = __builtin_convertvector(v, hwbf2_t); return __builtin_bit_cast(unsigned, b); }
; DI float lo16(unsigned w) { return __uint_as_float(w << 16); }
; DI float hi16(unsigned w) { return __uint_as_float(w & 0xffff0000u); }
; DI void gemm_epilogue(const GemmJob& J, const f32x4 (&acc)[2][2][4][2], const pg8::Unit& u, int wr, int wc, int fr, int fq) {
;     ...
; #pragma unroll
;         for (int it = 0; it < 8; ++it) { const int ai = it >> 2, m = it & 3; const int row = rloc0 + ai * 128 + m * 16;
;             if (it + 1 < 8) { const int rown = rloc0 + ((it + 1) >> 2) * 128 + ((it + 1) & 3) * 16; const float* gp = J.f1 + (size_t)modrow_of(J.row0 + rown) * 12288;
; #pragma unroll
;                 for (int q = 0; q < 4; ++q) { const int col = u.pn * 256 + (q >> 1) * 128 + wc * 32 + (q & 1) * 16 + 4 * fq; xb[(it + 1) & 1][q] = *(const u32x2*)(X + (size_t)rown * J.ld1 + col); gg[(it + 1) & 1][q] = *(const f32x4*)(gp + col); } }
;             __builtin_amdgcn_sched_barrier(0);
; #pragma unroll
;             for (int q = 0; q < 4; ++q) { const int bj = q >> 1, n = q & 1; const int col = u.pn * 256 + bj * 128 + wc * 32 + n * 16 + 4 * fq;
;                 const u32x2 xw = xb[it & 1][q]; const f32x4 xv = (f32x4){lo16(xw.x), hi16(xw.x), lo16(xw.y), hi16(xw.y)};
;                 const f32x4 o = xv * DN_ALPHA + (gg[it & 1][q] + 1.0f) * acc[ai][bj][m][n];
;                 u32x2 w; w.x = pk2(o[0], o[1]); w.y = pk2(o[2], o[3]); *(u32x2*)(X + (size_t)row * J.ld1 + col) = w; }
;             __builtin_amdgcn_sched_barrier(0); }
	v_cvt_pk_bf16_f32 v152, v152, v153
	v_cvt_pk_bf16_f32 v153, v154, v155
	global_store_dwordx2 v[228:229], v[152:153], off
	v_lshlrev_b32_e32 v152, 16, v232
	v_and_b32_e32 v153, 0xffff0000, v232
	v_lshlrev_b32_e32 v154, 16, v233
	v_and_b32_e32 v155, 0xffff0000, v233
	v_pk_mul_f32 v[152:153], v[152:153], s[10:11] op_sel_hi:[1,0]
	v_pk_mul_f32 v[154:155], v[154:155], s[10:11] op_sel_hi:[1,0]
	v_pk_add_f32 v[164:165], v[164:165], 1.0 op_sel_hi:[1,0]
	v_pk_fma_f32 v[154:155], v[84:85], v[166:167], v[154:155]
	v_pk_fma_f32 v[152:153], v[82:83], v[164:165], v[152:153]
	v_pk_add_f32 v[164:165], v[182:183], 1.0 op_sel_hi:[1,0]
	v_cvt_pk_bf16_f32 v152, v152, v153
	v_cvt_pk_bf16_f32 v153, v154, v155
	global_store_dwordx2 v[228:229], v[152:153], off offset:32
	v_lshlrev_b32_e32 v152, 16, v234
	v_and_b32_e32 v153, 0xffff0000, v234
	v_lshlrev_b32_e32 v154, 16, v235
	v_and_b32_e32 v155, 0xffff0000, v235
	v_pk_mul_f32 v[152:153], v[152:153], s[10:11] op_sel_hi:[1,0]
	v_pk_mul_f32 v[154:155], v[154:155], s[10:11] op_sel_hi:[1,0]
	v_pk_add_f32 v[166:167], v[180:181], 1.0 op_sel_hi:[1,0]
	v_pk_fma_f32 v[154:155], v[72:73], v[164:165], v[154:155]
	v_pk_fma_f32 v[152:153], v[70:71], v[166:167], v[152:153]
	v_pk_add_f32 v[164:165], v[186:187], 1.0 op_sel_hi:[1,0]
	v_cvt_pk_bf16_f32 v152, v152, v153
	v_cvt_pk_bf16_f32 v153, v154, v155
	global_store_dwordx2 v[228:229], v[152:153], off offset:256
	v_lshlrev_b32_e32 v152, 16, v236
	v_and_b32_e32 v153, 0xffff0000, v236
	v_lshlrev_b32_e32 v154, 16, v237
	v_and_b32_e32 v155, 0xffff0000, v237
	v_pk_mul_f32 v[152:153], v[152:153], s[10:11] op_sel_hi:[1,0]
	v_pk_mul_f32 v[154:155], v[154:155], s[10:11] op_sel_hi:[1,0]
	v_pk_add_f32 v[166:167], v[184:185], 1.0 op_sel_hi:[1,0]
	v_pk_fma_f32 v[154:155], v[68:69], v[164:165], v[154:155]
	v_pk_fma_f32 v[152:153], v[66:67], v[166:167], v[152:153]
	s_nop 0
	v_cvt_pk_bf16_f32 v152, v152, v153
	v_cvt_pk_bf16_f32 v153, v154, v155
	global_store_dwordx2 v[228:229], v[152:153], off offset:288
	v_add_u32_e32 v154, 0x90, v218
	v_add_u32_e32 v152, 0xffffc090, v218
	v_lshrrev_b32_e32 v152, 4, v152
	v_cmp_lt_i32_e32 vcc, s3, v154
	v_ashrrev_i32_e32 v165, 31, v154
	v_mad_u64_u32 v[154:155], s[30:31], v154, s27, 0
	v_add_u32_e32 v152, 1, v152
	v_mov_b32_e32 v164, v155
	v_cndmask_b32_e32 v152, 0, v152, vcc
	v_mad_u64_u32 v[164:165], s[30:31], v165, s27, v[164:165]
	v_mad_u64_u32 v[152:153], s[30:31], v152, s86, v[130:131]
	v_mov_b32_e32 v155, v164
	v_lshl_add_u64 v[154:155], v[154:155], 1, s[54:55]
	v_lshl_add_u64 v[184:185], v[152:153], 0, v[134:135]
	v_lshl_add_u64 v[228:229], v[154:155], 0, v[132:133]
	global_load_dwordx4 v[152:155], v[184:185], off
	global_load_dwordx4 v[164:167], v[184:185], off offset:64
	global_load_dwordx2 v[230:231], v[228:229], off
	global_load_dwordx2 v[232:233], v[228:229], off offset:32
	global_load_dwordx2 v[234:235], v[228:229], off offset:256
	global_load_dwordx2 v[236:237], v[228:229], off offset:288
	global_load_dwordx4 v[180:183], v[184:185], off offset:512
	s_nop 0
	global_load_dwordx4 v[184:187], v[184:185], off offset:576
	s_waitcnt vmcnt(0)
	v_lshlrev_b32_e32 v238, 16, v220
	v_and_b32_e32 v239, 0xffff0000, v220
	v_lshlrev_b32_e32 v220, 16, v221
	v_and_b32_e32 v221, 0xffff0000, v221
	v_pk_mul_f32 v[238:239], v[238:239], s[10:11] op_sel_hi:[1,0]
	v_pk_mul_f32 v[220:221], v[220:221], s[10:11] op_sel_hi:[1,0]
	v_pk_add_f32 v[138:139], v[138:139], 1.0 op_sel_hi:[1,0]
	v_pk_add_f32 v[136:137], v[136:137], 1.0 op_sel_hi:[1,0]
	v_pk_fma_f32 v[138:139], v[64:65], v[138:139], v[220:221]
	v_pk_fma_f32 v[136:137], v[62:63], v[136:137], v[238:239]
	v_pk_add_f32 v[142:143], v[142:143], 1.0 op_sel_hi:[1,0]
	v_cvt_pk_bf16_f32 v136, v136, v137
	v_cvt_pk_bf16_f32 v137, v138, v139
	global_store_dwordx2 v[156:157], v[136:137], off
	v_lshlrev_b32_e32 v136, 16, v222
	v_and_b32_e32 v137, 0xffff0000, v222
	v_lshlrev_b32_e32 v138, 16, v223
	v_and_b32_e32 v139, 0xffff0000, v223
	v_pk_mul_f32 v[136:137], v[136:137], s[10:11] op_sel_hi:[1,0]
	v_pk_mul_f32 v[138:139], v[138:139], s[10:11] op_sel_hi:[1,0]
	v_pk_add_f32 v[140:141], v[140:141], 1.0 op_sel_hi:[1,0]
	v_pk_fma_f32 v[138:139], v[60:61], v[142:143], v[138:139]
	v_pk_fma_f32 v[136:137], v[58:59], v[140:141], v[136:137]
	v_pk_add_f32 v[140:141], v[146:147], 1.0 op_sel_hi:[1,0]
	v_cvt_pk_bf16_f32 v136, v136, v137
	v_cvt_pk_bf16_f32 v137, v138, v139
	global_store_dwordx2 v[156:157], v[136:137], off offset:32
	v_lshlrev_b32_e32 v136, 16, v224
	v_and_b32_e32 v137, 0xffff0000, v224
	v_lshlrev_b32_e32 v138, 16, v225
	v_and_b32_e32 v139, 0xffff0000, v225
	v_pk_mul_f32 v[136:137], v[136:137], s[10:11] op_sel_hi:[1,0]
	v_pk_mul_f32 v[138:139], v[138:139], s[10:11] op_sel_hi:[1,0]
	v_pk_add_f32 v[142:143], v[144:145], 1.0 op_sel_hi:[1,0]
	v_pk_fma_f32 v[138:139], v[48:49], v[140:141], v[138:139]
	v_pk_fma_f32 v[136:137], v[46:47], v[142:143], v[136:137]
	v_pk_add_f32 v[140:141], v[150:151], 1.0 op_sel_hi:[1,0]
	v_cvt_pk_bf16_f32 v136, v136, v137
	v_cvt_pk_bf16_f32 v137, v138, v139
	global_store_dwordx2 v[156:157], v[136:137], off offset:256
	v_lshlrev_b32_e32 v136, 16, v226
	v_and_b32_e32 v137, 0xffff0000, v226
	v_lshlrev_b32_e32 v138, 16, v227
	v_and_b32_e32 v139, 0xffff0000, v227
	v_pk_mul_f32 v[136:137], v[136:137], s[10:11] op_sel_hi:[1,0]
	v_pk_mul_f32 v[138:139], v[138:139], s[10:11] op_sel_hi:[1,0]
	v_pk_add_f32 v[142:143], v[148:149], 1.0 op_sel_hi:[1,0]
	v_pk_fma_f32 v[138:139], v[44:45], v[140:141], v[138:139]
	v_pk_fma_f32 v[136:137], v[42:43], v[142:143], v[136:137]
	s_nop 0
	v_cvt_pk_bf16_f32 v136, v136, v137
	v_cvt_pk_bf16_f32 v137, v138, v139
	global_store_dwordx2 v[156:157], v[136:137], off offset:288
; DI unsigned pk2(float lo, float hi) { const hwf2_t v = {lo, hi}; const hwbf2_t b = __builtin_convertvector(v, hwbf2_t); return __builtin_bit_cast(unsigned, b); }
; DI float lo16(unsigned w) { return __uint_as_float(w << 16); }
; DI float hi16(unsigned w) { return __uint_as_float(w & 0xffff0000u); }
; DI void gemm_epilogue(const GemmJob& J, const f32x4 (&acc)[2][2][4][2], const pg8::Unit& u, int wr, int wc, int fr, int fq) {
;     ...
; #pragma unroll
;         for (int it = 0; it < 8; ++it) { const int ai = it >> 2, m = it & 3; const int row = rloc0 + ai * 128 + m * 16;
;             if (it + 1 < 8) { const int rown = rloc0 + ((it + 1) >> 2) * 128 + ((it + 1) & 3) * 16; const float* gp = J.f1 + (size_t)modrow_of(J.row0 + rown) * 12288;
; #pragma unroll
;                 for (int q = 0; q < 4; ++q) { const int col = u.pn * 256 + (q >> 1) * 128 + wc * 32 + (q & 1) * 16 + 4 * fq; xb[(it + 1) & 1][q] = *(const u32x2*)(X + (size_t)rown * J.ld1 + col); gg[(it + 1) & 1][q] = *(const f32x4*)(gp + col); } }
;             __builtin_amdgcn_sched_barrier(0);
; #pragma unroll
;             for (int q = 0; q < 4; ++q) { const int bj = q >> 1, n = q & 1; const int col = u.pn * 256 + bj * 128 + wc * 32 + n * 16 + 4 * fq;
;                 const u32x2 xw = xb[it & 1][q]; const f32x4 xv = (f32x4){lo16(xw.x), hi16(xw.x), lo16(xw.y), hi16(xw.y)};
;                 const f32x4 o = xv * DN_ALPHA + (gg[it & 1][q] + 1.0f) * acc[ai][bj][m][n];
;                 u32x2 w; w.x = pk2(o[0], o[1]); w.y = pk2(o[2], o[3]); *(u32x2*)(X + (size_t)row * J.ld1 + col) = w; }
;             __builtin_amdgcn_sched_barrier(0); }
	v_add_u32_e32 v138, 0xa0, v218
	v_add_u32_e32 v136, 0xffffc0a0, v218
	v_lshrrev_b32_e32 v136, 4, v136
	v_cmp_lt_i32_e32 vcc, s3, v138
	v_ashrrev_i32_e32 v141, 31, v138
	v_mad_u64_u32 v[138:139], s[30:31], v138, s27, 0
	v_or_b32_e32 v136, 1, v136
	v_mov_b32_e32 v140, v139
	v_cndmask_b32_e32 v136, 0, v136, vcc
	v_mad_u64_u32 v[140:141], s[30:31], v141, s27, v[140:141]
	v_mad_u64_u32 v[136:137], s[30:31], v136, s86, v[130:131]
	v_mov_b32_e32 v139, v140
	v_lshl_add_u64 v[138:139], v[138:139], 1, s[54:55]
	v_lshl_add_u64 v[148:149], v[136:137], 0, v[134:135]
	v_lshl_add_u64 v[156:157], v[138:139], 0, v[132:133]
	global_load_dwordx4 v[136:139], v[148:149], off
	global_load_dwordx4 v[140:143], v[148:149], off offset:64
	global_load_dwordx2 v[220:221], v[156:157], off
	global_load_dwordx2 v[222:223], v[156:157], off offset:32
	global_load_dwordx2 v[224:225], v[156:157], off offset:256
	global_load_dwordx2 v[226:227], v[156:157], off offset:288
	global_load_dwordx4 v[144:147], v[148:149], off offset:512
	s_nop 0
	global_load_dwordx4 v[148:151], v[148:149], off offset:576
	v_lshlrev_b32_e32 v238, 16, v230
	v_and_b32_e32 v239, 0xffff0000, v230
	v_lshlrev_b32_e32 v230, 16, v231
	v_and_b32_e32 v231, 0xffff0000, v231
	v_pk_mul_f32 v[238:239], v[238:239], s[10:11] op_sel_hi:[1,0]
	v_pk_mul_f32 v[230:231], v[230:231], s[10:11] op_sel_hi:[1,0]
	v_pk_add_f32 v[154:155], v[154:155], 1.0 op_sel_hi:[1,0]
	v_pk_add_f32 v[152:153], v[152:153], 1.0 op_sel_hi:[1,0]
	v_pk_fma_f32 v[154:155], v[56:57], v[154:155], v[230:231]
	v_pk_fma_f32 v[152:153], v[54:55], v[152:153], v[238:239]
	v_pk_add_f32 v[166:167], v[166:167], 1.0 op_sel_hi:[1,0]
	v_cvt_pk_bf16_f32 v152, v152, v153
	v_cvt_pk_bf16_f32 v153, v154, v155
	global_store_dwordx2 v[228:229], v[152:153], off
	v_lshlrev_b32_e32 v152, 16, v232
	v_and_b32_e32 v153, 0xffff0000, v232
	v_lshlrev_b32_e32 v154, 16, v233
	v_and_b32_e32 v155, 0xffff0000, v233
	v_pk_mul_f32 v[152:153], v[152:153], s[10:11] op_sel_hi:[1,0]
	v_pk_mul_f32 v[154:155], v[154:155], s[10:11] op_sel_hi:[1,0]
	v_pk_add_f32 v[164:165], v[164:165], 1.0 op_sel_hi:[1,0]
	v_pk_fma_f32 v[154:155], v[52:53], v[166:167], v[154:155]
	v_pk_fma_f32 v[152:153], v[50:51], v[164:165], v[152:153]
	v_pk_add_f32 v[164:165], v[182:183], 1.0 op_sel_hi:[1,0]
	v_cvt_pk_bf16_f32 v152, v152, v153
	v_cvt_pk_bf16_f32 v153, v154, v155
	global_store_dwordx2 v[228:229], v[152:153], off offset:32
	v_lshlrev_b32_e32 v152, 16, v234
	v_and_b32_e32 v153, 0xffff0000, v234
	v_lshlrev_b32_e32 v154, 16, v235
	v_and_b32_e32 v155, 0xffff0000, v235
	v_pk_mul_f32 v[152:153], v[152:153], s[10:11] op_sel_hi:[1,0]
	v_pk_mul_f32 v[154:155], v[154:155], s[10:11] op_sel_hi:[1,0]
	v_pk_add_f32 v[166:167], v[180:181], 1.0 op_sel_hi:[1,0]
	v_pk_fma_f32 v[154:155], v[32:33], v[164:165], v[154:155]
	v_pk_fma_f32 v[152:153], v[30:31], v[166:167], v[152:153]
	v_pk_add_f32 v[164:165], v[186:187], 1.0 op_sel_hi:[1,0]
	v_cvt_pk_bf16_f32 v152, v152, v153
	v_cvt_pk_bf16_f32 v153, v154, v155
	global_store_dwordx2 v[228:229], v[152:153], off offset:256
	v_lshlrev_b32_e32 v152, 16, v236
	v_and_b32_e32 v153, 0xffff0000, v236
	v_lshlrev_b32_e32 v154, 16, v237
	v_and_b32_e32 v155, 0xffff0000, v237
	v_pk_mul_f32 v[152:153], v[152:153], s[10:11] op_sel_hi:[1,0]
	v_pk_mul_f32 v[154:155], v[154:155], s[10:11] op_sel_hi:[1,0]
	v_pk_add_f32 v[166:167], v[184:185], 1.0 op_sel_hi:[1,0]
	v_pk_fma_f32 v[154:155], v[28:29], v[164:165], v[154:155]
	v_pk_fma_f32 v[152:153], v[26:27], v[166:167], v[152:153]
	s_nop 0
	v_cvt_pk_bf16_f32 v152, v152, v153
	v_cvt_pk_bf16_f32 v153, v154, v155
	global_store_dwordx2 v[228:229], v[152:153], off offset:288
	v_add_u32_e32 v153, 0xffffc0b0, v218
	v_add_u32_e32 v152, 0xb0, v218
	v_lshrrev_b32_e32 v153, 4, v153
	v_add_u32_e32 v153, 1, v153
	v_cmp_lt_i32_e32 vcc, s3, v152
	v_ashrrev_i32_e32 v155, 31, v152
	s_nop 0
	v_cndmask_b32_e32 v153, 0, v153, vcc
	v_mad_u64_u32 v[130:131], s[30:31], v153, s86, v[130:131]
	v_mad_u64_u32 v[152:153], s[30:31], v152, s27, 0
	v_mov_b32_e32 v154, v153
	v_mad_u64_u32 v[154:155], s[30:31], v155, s27, v[154:155]
	v_mov_b32_e32 v153, v154
	v_lshl_add_u64 v[152:153], v[152:153], 1, s[54:55]
	v_lshl_add_u64 v[134:135], v[130:131], 0, v[134:135]
	v_lshl_add_u64 v[184:185], v[152:153], 0, v[132:133]
	global_load_dwordx4 v[130:133], v[134:135], off
	global_load_dwordx4 v[152:155], v[134:135], off offset:64
	global_load_dwordx2 v[186:187], v[184:185], off
	global_load_dwordx2 v[228:229], v[184:185], off offset:32
	global_load_dwordx2 v[230:231], v[184:185], off offset:256
	global_load_dwordx2 v[232:233], v[184:185], off offset:288
	global_load_dwordx4 v[164:167], v[134:135], off offset:512
	global_load_dwordx4 v[180:183], v[134:135], off offset:576
	s_waitcnt vmcnt(0)
; DI unsigned pk2(float lo, float hi) { const hwf2_t v = {lo, hi}; const hwbf2_t b = __builtin_convertvector(v, hwbf2_t); return __builtin_bit_cast(unsigned, b); }
; DI float lo16(unsigned w) { return __uint_as_float(w << 16); }
; DI float hi16(unsigned w) { return __uint_as_float(w & 0xffff0000u); }
; DI void gemm_epilogue(const GemmJob& J, const f32x4 (&acc)[2][2][4][2], const pg8::Unit& u, int wr, int wc, int fr, int fq) {
;     ...
;             __builtin_amdgcn_sched_barrier(0);
; #pragma unroll
;             for (int q = 0; q < 4; ++q) { const int bj = q >> 1, n = q & 1; const int col = u.pn * 256 + bj * 128 + wc * 32 + n * 16 + 4 * fq;
;                 const u32x2 xw = xb[it & 1][q]; const f32x4 xv = (f32x4){lo16(xw.x), hi16(xw.x), lo16(xw.y), hi16(xw.y)};
;                 const f32x4 o = xv * DN_ALPHA + (gg[it & 1][q] + 1.0f) * acc[ai][bj][m][n];
;                 u32x2 w; w.x = pk2(o[0], o[1]); w.y = pk2(o[2], o[3]); *(u32x2*)(X + (size_t)row * J.ld1 + col) = w; }
;             __builtin_amdgcn_sched_barrier(0); }
	v_lshlrev_b32_e32 v134, 16, v220
	v_and_b32_e32 v135, 0xffff0000, v220
	v_lshlrev_b32_e32 v220, 16, v221
	v_and_b32_e32 v221, 0xffff0000, v221
	v_pk_mul_f32 v[134:135], v[134:135], s[10:11] op_sel_hi:[1,0]
	v_pk_mul_f32 v[220:221], v[220:221], s[10:11] op_sel_hi:[1,0]
	v_pk_add_f32 v[138:139], v[138:139], 1.0 op_sel_hi:[1,0]
	v_pk_add_f32 v[136:137], v[136:137], 1.0 op_sel_hi:[1,0]
	v_pk_fma_f32 v[138:139], v[40:41], v[138:139], v[220:221]
	v_pk_fma_f32 v[134:135], v[38:39], v[136:137], v[134:135]
	v_lshlrev_b32_e32 v136, 16, v223
	v_cvt_pk_bf16_f32 v134, v134, v135
	v_cvt_pk_bf16_f32 v135, v138, v139
	global_store_dwordx2 v[156:157], v[134:135], off
	v_lshlrev_b32_e32 v134, 16, v222
	v_and_b32_e32 v135, 0xffff0000, v222
	v_and_b32_e32 v137, 0xffff0000, v223
	v_pk_mul_f32 v[134:135], v[134:135], s[10:11] op_sel_hi:[1,0]
	v_pk_mul_f32 v[136:137], v[136:137], s[10:11] op_sel_hi:[1,0]
	v_pk_add_f32 v[138:139], v[142:143], 1.0 op_sel_hi:[1,0]
	v_pk_add_f32 v[140:141], v[140:141], 1.0 op_sel_hi:[1,0]
	v_pk_fma_f32 v[136:137], v[36:37], v[138:139], v[136:137]
	v_pk_fma_f32 v[134:135], v[34:35], v[140:141], v[134:135]
	v_pk_add_f32 v[138:139], v[146:147], 1.0 op_sel_hi:[1,0]
	v_cvt_pk_bf16_f32 v134, v134, v135
	v_cvt_pk_bf16_f32 v135, v136, v137
	global_store_dwordx2 v[156:157], v[134:135], off offset:32
	v_lshlrev_b32_e32 v134, 16, v224
	v_and_b32_e32 v135, 0xffff0000, v224
	v_lshlrev_b32_e32 v136, 16, v225
	v_and_b32_e32 v137, 0xffff0000, v225
	v_pk_mul_f32 v[134:135], v[134:135], s[10:11] op_sel_hi:[1,0]
	v_pk_mul_f32 v[136:137], v[136:137], s[10:11] op_sel_hi:[1,0]
	v_pk_add_f32 v[140:141], v[144:145], 1.0 op_sel_hi:[1,0]
	v_pk_fma_f32 v[136:137], v[16:17], v[138:139], v[136:137]
	v_pk_fma_f32 v[134:135], v[14:15], v[140:141], v[134:135]
	v_pk_add_f32 v[138:139], v[150:151], 1.0 op_sel_hi:[1,0]
	v_cvt_pk_bf16_f32 v134, v134, v135
	v_cvt_pk_bf16_f32 v135, v136, v137
	global_store_dwordx2 v[156:157], v[134:135], off offset:256
	v_lshlrev_b32_e32 v134, 16, v226
	v_and_b32_e32 v135, 0xffff0000, v226
	v_lshlrev_b32_e32 v136, 16, v227
	v_and_b32_e32 v137, 0xffff0000, v227
	v_pk_mul_f32 v[134:135], v[134:135], s[10:11] op_sel_hi:[1,0]
	v_pk_mul_f32 v[136:137], v[136:137], s[10:11] op_sel_hi:[1,0]
	v_pk_add_f32 v[140:141], v[148:149], 1.0 op_sel_hi:[1,0]
	v_pk_fma_f32 v[136:137], v[12:13], v[138:139], v[136:137]
	v_pk_fma_f32 v[134:135], v[10:11], v[140:141], v[134:135]
	s_nop 0
	v_cvt_pk_bf16_f32 v134, v134, v135
	v_cvt_pk_bf16_f32 v135, v136, v137
	global_store_dwordx2 v[156:157], v[134:135], off offset:288
	v_lshlrev_b32_e32 v134, 16, v186
	v_and_b32_e32 v135, 0xffff0000, v186
	v_lshlrev_b32_e32 v136, 16, v187
	v_and_b32_e32 v137, 0xffff0000, v187
	v_pk_mul_f32 v[134:135], v[134:135], s[10:11] op_sel_hi:[1,0]
	v_pk_mul_f32 v[136:137], v[136:137], s[10:11] op_sel_hi:[1,0]
	v_pk_add_f32 v[132:133], v[132:133], 1.0 op_sel_hi:[1,0]
	v_pk_add_f32 v[130:131], v[130:131], 1.0 op_sel_hi:[1,0]
	v_pk_fma_f32 v[132:133], v[24:25], v[132:133], v[136:137]
	v_pk_fma_f32 v[130:131], v[22:23], v[130:131], v[134:135]
	v_pk_add_f32 v[134:135], v[154:155], 1.0 op_sel_hi:[1,0]
	v_cvt_pk_bf16_f32 v130, v130, v131
	v_cvt_pk_bf16_f32 v131, v132, v133
	global_store_dwordx2 v[184:185], v[130:131], off
	v_lshlrev_b32_e32 v130, 16, v228
	v_and_b32_e32 v131, 0xffff0000, v228
	v_lshlrev_b32_e32 v132, 16, v229
	v_and_b32_e32 v133, 0xffff0000, v229
	v_pk_mul_f32 v[130:131], v[130:131], s[10:11] op_sel_hi:[1,0]
	v_pk_mul_f32 v[132:133], v[132:133], s[10:11] op_sel_hi:[1,0]
	v_pk_add_f32 v[136:137], v[152:153], 1.0 op_sel_hi:[1,0]
	v_pk_fma_f32 v[132:133], v[20:21], v[134:135], v[132:133]
	v_pk_fma_f32 v[130:131], v[18:19], v[136:137], v[130:131]
	v_pk_add_f32 v[134:135], v[166:167], 1.0 op_sel_hi:[1,0]
	v_cvt_pk_bf16_f32 v130, v130, v131
	v_cvt_pk_bf16_f32 v131, v132, v133
	global_store_dwordx2 v[184:185], v[130:131], off offset:32
	v_lshlrev_b32_e32 v130, 16, v230
	v_and_b32_e32 v131, 0xffff0000, v230
	v_lshlrev_b32_e32 v132, 16, v231
	v_and_b32_e32 v133, 0xffff0000, v231
	v_pk_mul_f32 v[130:131], v[130:131], s[10:11] op_sel_hi:[1,0]
	v_pk_mul_f32 v[132:133], v[132:133], s[10:11] op_sel_hi:[1,0]
	v_pk_add_f32 v[136:137], v[164:165], 1.0 op_sel_hi:[1,0]
	v_pk_fma_f32 v[132:133], v[8:9], v[134:135], v[132:133]
	v_pk_fma_f32 v[130:131], v[6:7], v[136:137], v[130:131]
	v_pk_add_f32 v[134:135], v[182:183], 1.0 op_sel_hi:[1,0]
	v_cvt_pk_bf16_f32 v130, v130, v131
	v_cvt_pk_bf16_f32 v131, v132, v133
	global_store_dwordx2 v[184:185], v[130:131], off offset:256
	v_lshlrev_b32_e32 v130, 16, v232
	v_and_b32_e32 v131, 0xffff0000, v232
	v_lshlrev_b32_e32 v132, 16, v233
	v_and_b32_e32 v133, 0xffff0000, v233
	v_pk_mul_f32 v[130:131], v[130:131], s[10:11] op_sel_hi:[1,0]
	v_pk_mul_f32 v[132:133], v[132:133], s[10:11] op_sel_hi:[1,0]
	v_pk_add_f32 v[136:137], v[180:181], 1.0 op_sel_hi:[1,0]
	v_pk_fma_f32 v[132:133], v[4:5], v[134:135], v[132:133]
	v_pk_fma_f32 v[130:131], v[2:3], v[136:137], v[130:131]
	s_nop 0
	v_cvt_pk_bf16_f32 v130, v130, v131
	v_cvt_pk_bf16_f32 v131, v132, v133
	global_store_dwordx2 v[184:185], v[130:131], off offset:288
	s_mov_b64 s[42:43], 0
; DI void gemm_epilogue(const GemmJob& J, const f32x4 (&acc)[2][2][4][2], const pg8::Unit& u, int wr, int wc, int fr, int fq) {
;     ...
;     } else if (J.mode == 2) {
;         bf16_t* MG = (bf16_t*)J.o1; const bf16_t* Gt = (const bf16_t*)J.o2; const int col0 = u.pn * 256 + wc * 32 + 8 * fq;
;         u32x4 gb[2][2], pb[2][2];
; #pragma unroll
;         for (int bj = 0; bj < 2; ++bj) { gb[0][bj] = *(const u32x4*)(Gt + (size_t)rloc0 * J.ld2 + col0 + bj * 128); pb[0][bj] = (u32x4){0u, 0u, 0u, 0u};
;             if (!J.flag) pb[0][bj] = *(const u32x4*)(MG + (size_t)rloc0 * J.ld1 + col0 + bj * 128); }
; #pragma unroll
;         for (int it = 0; it < 8; ++it) { const int ai = it >> 2, m = it & 3; const int row = rloc0 + ai * 128 + m * 16;
;             if (it + 1 < 8) { const int rown = rloc0 + ((it + 1) >> 2) * 128 + ((it + 1) & 3) * 16;
; #pragma unroll
;                 for (int bj = 0; bj < 2; ++bj) { gb[(it + 1) & 1][bj] = *(const u32x4*)(Gt + (size_t)rown * J.ld2 + col0 + bj * 128); pb[(it + 1) & 1][bj] = (u32x4){0u, 0u, 0u, 0u};
;                     if (!J.flag) pb[(it + 1) & 1][bj] = *(const u32x4*)(MG + (size_t)rown * J.ld1 + col0 + bj * 128); } }
.LBB0_100:
	s_andn2_b64 vcc, exec, s[42:43]
	s_cbranch_vccnz .LBB0_134
	v_mad_u64_u32 v[132:133], s[30:31], v218, s75, 0
	v_ashrrev_i32_e32 v219, 31, v218
	v_mov_b32_e32 v134, v133
	v_lshl_or_b32 v130, s84, 8, v215
	v_mad_u64_u32 v[134:135], s[30:31], v219, s75, v[134:135]
	v_mov_b32_e32 v133, v134
	v_ashrrev_i32_e32 v131, 31, v130
	v_lshl_add_u64 v[132:133], v[132:133], 1, s[64:65]
	v_lshlrev_b64 v[134:135], 1, v[130:131]
	v_lshl_add_u64 v[132:133], v[132:133], 0, v[134:135]
	global_load_dwordx4 v[164:167], v[132:133], off
	v_lshl_add_u64 v[180:181], s[54:55], 0, v[134:135]
	v_mad_u64_u32 v[134:135], s[30:31], v218, s27, 0
	v_mov_b32_e32 v136, v135
	v_mad_u64_u32 v[136:137], s[30:31], v219, s27, v[136:137]
	v_mov_b32_e32 v135, v136
	v_lshl_add_u64 v[186:187], v[134:135], 1, v[180:181]
	s_mov_b64 s[30:31], 0x18000
	v_lshl_add_u64 v[240:241], v[132:133], 0, s[30:31]
	global_load_dword v239, v[240:241], off
	global_load_dword v239, v[240:241], off offset:256
	s_mov_b64 s[30:31], 0x8000
	v_lshl_add_u64 v[240:241], v[186:187], 0, s[30:31]
	global_load_dword v239, v[240:241], off
	global_load_dword v239, v[240:241], off offset:256
	s_mov_b64 s[30:31], 0x30000
	v_lshl_add_u64 v[240:241], v[132:133], 0, s[30:31]
	global_load_dword v239, v[240:241], off
	global_load_dword v239, v[240:241], off offset:256
	s_mov_b64 s[30:31], 0x10000
	v_lshl_add_u64 v[240:241], v[186:187], 0, s[30:31]
	global_load_dword v239, v[240:241], off
	global_load_dword v239, v[240:241], off offset:256
	s_mov_b64 s[30:31], 0x48000
	v_lshl_add_u64 v[240:241], v[132:133], 0, s[30:31]
	global_load_dword v239, v[240:241], off
	global_load_dword v239, v[240:241], off offset:256
	s_mov_b64 s[30:31], 0x18000
	v_lshl_add_u64 v[240:241], v[186:187], 0, s[30:31]
	global_load_dword v239, v[240:241], off
	global_load_dword v239, v[240:241], off offset:256
	s_mov_b64 s[30:31], 0xc0000
	v_lshl_add_u64 v[240:241], v[132:133], 0, s[30:31]
	global_load_dword v239, v[240:241], off
	global_load_dword v239, v[240:241], off offset:256
	s_mov_b64 s[30:31], 0x40000
	v_lshl_add_u64 v[240:241], v[186:187], 0, s[30:31]
	global_load_dword v239, v[240:241], off
	global_load_dword v239, v[240:241], off offset:256
	s_mov_b64 s[30:31], 0xd8000
	v_lshl_add_u64 v[240:241], v[132:133], 0, s[30:31]
	global_load_dword v239, v[240:241], off
	global_load_dword v239, v[240:241], off offset:256
	s_mov_b64 s[30:31], 0x48000
	v_lshl_add_u64 v[240:241], v[186:187], 0, s[30:31]
	global_load_dword v239, v[240:241], off
	global_load_dword v239, v[240:241], off offset:256
	s_mov_b64 s[30:31], 0xf0000
	v_lshl_add_u64 v[240:241], v[132:133], 0, s[30:31]
	global_load_dword v239, v[240:241], off
	global_load_dword v239, v[240:241], off offset:256
	s_mov_b64 s[30:31], 0x50000
	v_lshl_add_u64 v[240:241], v[186:187], 0, s[30:31]
	global_load_dword v239, v[240:241], off
	global_load_dword v239, v[240:241], off offset:256
	s_mov_b64 s[30:31], 0x108000
	v_lshl_add_u64 v[240:241], v[132:133], 0, s[30:31]
	global_load_dword v239, v[240:241], off
	global_load_dword v239, v[240:241], off offset:256
	s_mov_b64 s[30:31], 0x58000
	v_lshl_add_u64 v[240:241], v[186:187], 0, s[30:31]
	global_load_dword v239, v[240:241], off
	global_load_dword v239, v[240:241], off offset:256
	v_cndmask_b32_e64 v135, 0, 1, s[38:39]
	v_mov_b32_e32 v134, 0
	v_cmp_ne_u32_e64 s[42:43], 1, v135
	s_andn2_b64 vcc, exec, s[38:39]
	v_mov_b32_e32 v150, 0
	v_mov_b32_e32 v151, 0
	v_mov_b32_e32 v152, 0
	v_mov_b32_e32 v153, 0
	s_cbranch_vccnz .LBB0_103
	global_load_dwordx4 v[150:153], v[186:187], off
